# HG_H3 fourth MFMA block: sixteen fragment reads issued ahead into own registers, counted lgkmcnt waits
# baseline (speedup 1.0000x reference)
; #define LAS __attribute__((address_space(3)))
; __device__ __forceinline__ unsigned pk2(float lo, float hi) { f32x2c v = {lo, hi}; return __builtin_bit_cast(unsigned, __builtin_convertvector(v, bf16x2c)); }
; __device__ __forceinline__ void hgrn_h3(LAS unsigned char* lds8, const int e) {
;     ...
;         const int fr = lane & 15, fq = lane >> 4;
;         f32x4 acc[4];
; #pragma unroll
;         for (int I = 0; I < 4; ++I) acc[I] = (f32x4){0.f, 0.f, 0.f, 0.f};
; #pragma unroll
;         for (int ks = 0; ks < 4; ++ks) { const bf16x8 a = *(const LAS bf16x8*)(ST + (16 * wave + fr) * RS128 + 32 * ks + 8 * fq);
; #pragma unroll
;             for (int I = 0; I < 4; ++I) { const bf16x8 bb = *(const LAS bf16x8*)(Qb + (16 * I + fr) * RS128 + 32 * ks + 8 * fq);
;                 acc[I] = __builtin_amdgcn_mfma_f32_16x16x32_bf16(a, bb, acc[I], 0, 0, 0); } }
; #pragma unroll
;         for (int I = 0; I < 4; ++I) {
;             const int rb = 8 * I * (I + 1);
;             f32x4 P[4];
; #pragma unroll
;             for (int Jt = 0; Jt < 4; ++Jt) { P[Jt] = (f32x4){0.f, 0.f, 0.f, 0.f};
;                 if (Jt <= I) {
; #pragma unroll
;                     for (int ks = 0; ks < 4; ++ks) { const bf16x8 a = *(const LAS bf16x8*)(KT + (rb + 16 * Jt + fr) * RS128 + 32 * ks + 8 * fq);
;                         const bf16x8 bb = *(const LAS bf16x8*)(Qt + (16 * I + fr) * RS128 + 32 * ks + 8 * fq);
;                         P[Jt] = __builtin_amdgcn_mfma_f32_16x16x32_bf16(a, bb, P[Jt], 0, 0, 0); }
;                     if (Jt == I) {
; #pragma unroll
;                         for (int r = 0; r < 4; ++r) P[Jt][r] = (4 * fq + r <= fr) ? P[Jt][r] : 0.f; }
;                 } }
; #pragma unroll
;             for (int s = 0; s < 2; ++s) if (2 * s <= I) {
;                 u32x4 pw; pw.x = pk2(P[2 * s][0], P[2 * s][1]); pw.y = pk2(P[2 * s][2], P[2 * s][3]); pw.z = pk2(P[2 * s + 1][0], P[2 * s + 1][1]); pw.w = pk2(P[2 * s + 1][2], P[2 * s + 1][3]);
;                 const s16x4 v0 = *(const LAS s16x4*)(VT + (16 * wave + fr) * RS64 + 32 * s + 4 * fq), v1 = *(const LAS s16x4*)(VT + (16 * wave + fr) * RS64 + 32 * s + 16 + 4 * fq);
;                 const bf16x8 a = (bf16x8){v0[0], v0[1], v0[2], v0[3], v1[0], v1[1], v1[2], v1[3]};
;                 acc[I] = __builtin_amdgcn_mfma_f32_16x16x32_bf16(a, __builtin_bit_cast(bf16x8, pw), acc[I], 0, 0, 0); }
.LBB0_754:
	s_or_b64 exec, exec, s[30:31]
	s_waitcnt lgkmcnt(0)
	s_barrier
	ds_read_b128 v[4:7], v53
	ds_read_b128 v[8:11], v79 offset:17408
	ds_read_b128 v[12:15], v79 offset:21760
	ds_read_b128 v[16:19], v79 offset:26112
	ds_read_b128 v[20:23], v79 offset:30464
	ds_read_b128 v[192:195], v53 offset:64
	ds_read_b128 v[196:199], v79 offset:17472
	ds_read_b128 v[200:203], v79 offset:21824
	ds_read_b128 v[204:207], v79 offset:26176
	ds_read_b128 v[208:211], v79 offset:30528
	ds_read_b128 v[212:215], v53 offset:128
	ds_read_b128 v[216:219], v79 offset:17536
	ds_read_b128 v[220:223], v79 offset:21888
	ds_read_b128 v[224:227], v79 offset:26240
	ds_read_b128 v[228:231], v79 offset:30592
	s_waitcnt lgkmcnt(13)
	v_mfma_f32_16x16x32_bf16 v[8:11], v[4:7], v[8:11], 0
	s_add_i32 s66, s66, s46
	s_add_i32 s4, s4, s5
	s_add_i32 s28, s28, s34
	s_waitcnt lgkmcnt(12)
	v_mfma_f32_16x16x32_bf16 v[12:15], v[4:7], v[12:15], 0
	v_lshl_add_u64 v[32:33], v[32:33], 0, s[2:3]
	s_cmpk_lt_i32 s66, 0x400
	s_waitcnt lgkmcnt(11)
	v_mfma_f32_16x16x32_bf16 v[16:19], v[4:7], v[16:19], 0
	s_waitcnt lgkmcnt(10)
	v_mfma_f32_16x16x32_bf16 v[4:7], v[4:7], v[20:23], 0
	ds_read_b128 v[236:239], v53 offset:192
	ds_read_b128 v[240:243], v79 offset:17600
	ds_read_b128 v[244:247], v79 offset:21952
	s_waitcnt lgkmcnt(11)
	v_mfma_f32_16x16x32_bf16 v[8:11], v[192:195], v[196:199], v[8:11]
	s_waitcnt lgkmcnt(10)
	v_mfma_f32_16x16x32_bf16 v[12:15], v[192:195], v[200:203], v[12:15]
	s_waitcnt lgkmcnt(9)
	v_mfma_f32_16x16x32_bf16 v[16:19], v[192:195], v[204:207], v[16:19]
	s_waitcnt lgkmcnt(8)
	v_mfma_f32_16x16x32_bf16 v[4:7], v[192:195], v[208:211], v[4:7]
	s_waitcnt lgkmcnt(6)
	v_mfma_f32_16x16x32_bf16 v[8:11], v[212:215], v[216:219], v[8:11]
	s_waitcnt lgkmcnt(5)
	v_mfma_f32_16x16x32_bf16 v[12:15], v[212:215], v[220:223], v[12:15]
	s_waitcnt lgkmcnt(4)
	v_mfma_f32_16x16x32_bf16 v[16:19], v[212:215], v[224:227], v[16:19]
	s_waitcnt lgkmcnt(3)
	v_mfma_f32_16x16x32_bf16 v[4:7], v[212:215], v[228:231], v[4:7]
	s_waitcnt lgkmcnt(1)
	v_mfma_f32_16x16x32_bf16 v[8:11], v[236:239], v[240:243], v[8:11]
	s_waitcnt lgkmcnt(0)
	v_mfma_f32_16x16x32_bf16 v[82:85], v[236:239], v[244:247], v[12:15]
	s_nop 2
	ds_read_b128 v[12:15], v79 offset:26304
	s_waitcnt lgkmcnt(0)
	v_mfma_f32_16x16x32_bf16 v[20:23], v[236:239], v[12:15], v[16:19]
	ds_read_b128 v[12:15], v79 offset:30656
	s_waitcnt lgkmcnt(0)
	v_mfma_f32_16x16x32_bf16 v[4:7], v[236:239], v[12:15], v[4:7]
	ds_read_b128 v[12:15], v79 offset:34816
	ds_read_b128 v[16:19], v79
	s_waitcnt lgkmcnt(0)
	v_mfma_f32_16x16x32_bf16 v[12:15], v[12:15], v[16:19], 0
	ds_read_b128 v[16:19], v79 offset:34880
	ds_read_b128 v[24:27], v79 offset:64
	s_waitcnt lgkmcnt(0)
	v_mfma_f32_16x16x32_bf16 v[12:15], v[16:19], v[24:27], v[12:15]
	ds_read_b128 v[16:19], v79 offset:34944
	ds_read_b128 v[24:27], v79 offset:128
	s_waitcnt lgkmcnt(0)
	v_mfma_f32_16x16x32_bf16 v[12:15], v[16:19], v[24:27], v[12:15]
	ds_read_b128 v[16:19], v79 offset:35008
	ds_read_b128 v[24:27], v79 offset:192
	s_waitcnt lgkmcnt(0)
	v_mfma_f32_16x16x32_bf16 v[12:15], v[16:19], v[24:27], v[12:15]
	v_mov_b32_e32 v18, v3
	v_mov_b32_e32 v19, v3
	s_nop 5
	v_cndmask_b32_e64 v12, v12, 0, s[20:21]
	v_cndmask_b32_e64 v13, 0, v13, s[22:23]
	v_cndmask_b32_e64 v14, v14, 0, s[24:25]
	v_cndmask_b32_e64 v15, v15, 0, s[26:27]
	v_cvt_pk_bf16_f32 v16, v12, v13
	v_cvt_pk_bf16_f32 v17, v14, v15
	ds_read2_b64 v[12:15], v81 offset1:4
	s_waitcnt lgkmcnt(0)
	v_mfma_f32_16x16x32_bf16 v[8:11], v[12:15], v[16:19], v[8:11]
	ds_read_b128 v[16:19], v79 offset:39168
	ds_read_b128 v[24:27], v79 offset:4352
	ds_read_b128 v[86:89], v79 offset:39232
	ds_read_b128 v[90:93], v79 offset:4416
	ds_read_b128 v[192:195], v79 offset:39296
	ds_read_b128 v[94:97], v79 offset:4480
	ds_read_b128 v[196:199], v79 offset:39360
	ds_read_b128 v[98:101], v79 offset:4544
	ds_read_b128 v[200:203], v79 offset:43520
	ds_read_b128 v[204:207], v79 offset:43584
	ds_read_b128 v[208:211], v79 offset:43648
	ds_read_b128 v[212:215], v79 offset:43712
	s_waitcnt lgkmcnt(10)
	v_mfma_f32_16x16x32_bf16 v[16:19], v[16:19], v[24:27], 0
	s_waitcnt lgkmcnt(8)
	v_mfma_f32_16x16x32_bf16 v[16:19], v[86:89], v[90:93], v[16:19]
	s_waitcnt lgkmcnt(6)
	v_mfma_f32_16x16x32_bf16 v[16:19], v[192:195], v[94:97], v[16:19]
	s_waitcnt lgkmcnt(4)
	v_mfma_f32_16x16x32_bf16 v[16:19], v[196:199], v[98:101], v[16:19]
	s_waitcnt lgkmcnt(3)
	v_mfma_f32_16x16x32_bf16 v[24:27], v[200:203], v[24:27], 0
	s_nop 4
	v_cvt_pk_bf16_f32 v16, v16, v17
	v_cvt_pk_bf16_f32 v17, v18, v19
	s_waitcnt lgkmcnt(2)
	v_mfma_f32_16x16x32_bf16 v[24:27], v[204:207], v[90:93], v[24:27]
	s_waitcnt lgkmcnt(1)
	v_mfma_f32_16x16x32_bf16 v[24:27], v[208:211], v[94:97], v[24:27]
	s_waitcnt lgkmcnt(0)
	v_mfma_f32_16x16x32_bf16 v[24:27], v[212:215], v[98:101], v[24:27]
	s_nop 7
	v_cndmask_b32_e64 v24, v24, 0, s[20:21]
	v_cndmask_b32_e64 v25, 0, v25, s[22:23]
	v_cndmask_b32_e64 v26, v26, 0, s[24:25]
	v_cndmask_b32_e64 v27, v27, 0, s[26:27]
	v_cvt_pk_bf16_f32 v18, v24, v25
	v_cvt_pk_bf16_f32 v19, v26, v27
	s_nop 1
	v_mfma_f32_16x16x32_bf16 v[16:19], v[12:15], v[16:19], v[82:85]
	ds_read_b128 v[24:27], v79 offset:47872
	s_nop 1
	ds_read_b128 v[82:85], v79 offset:8704
	ds_read_b128 v[86:89], v79 offset:47936
	ds_read_b128 v[90:93], v79 offset:8768
	ds_read_b128 v[192:195], v79 offset:48000
	ds_read_b128 v[94:97], v79 offset:8832
	ds_read_b128 v[196:199], v79 offset:48064
	ds_read_b128 v[98:101], v79 offset:8896
	ds_read_b128 v[102:105], v79 offset:52288
	ds_read_b128 v[200:203], v79 offset:52224
	ds_read_b128 v[204:207], v79 offset:52352
	ds_read_b128 v[208:211], v79 offset:52416
	ds_read_b128 v[212:215], v79 offset:56576
	ds_read_b128 v[216:219], v79 offset:56640
	ds_read_b128 v[220:223], v79 offset:56704
	s_waitcnt lgkmcnt(13)
; #define LAS __attribute__((address_space(3)))
; __device__ __forceinline__ unsigned pk2(float lo, float hi) { f32x2c v = {lo, hi}; return __builtin_bit_cast(unsigned, __builtin_convertvector(v, bf16x2c)); }
; __device__ __forceinline__ void hgrn_h3(LAS unsigned char* lds8, const int e) {
;     ...
;         for (int I = 0; I < 4; ++I) {
;             const int rb = 8 * I * (I + 1);
;             f32x4 P[4];
; #pragma unroll
;             for (int Jt = 0; Jt < 4; ++Jt) { P[Jt] = (f32x4){0.f, 0.f, 0.f, 0.f};
;                 if (Jt <= I) {
; #pragma unroll
;                     for (int ks = 0; ks < 4; ++ks) { const bf16x8 a = *(const LAS bf16x8*)(KT + (rb + 16 * Jt + fr) * RS128 + 32 * ks + 8 * fq);
;                         const bf16x8 bb = *(const LAS bf16x8*)(Qt + (16 * I + fr) * RS128 + 32 * ks + 8 * fq);
;                         P[Jt] = __builtin_amdgcn_mfma_f32_16x16x32_bf16(a, bb, P[Jt], 0, 0, 0); }
;                     if (Jt == I) {
; #pragma unroll
;                         for (int r = 0; r < 4; ++r) P[Jt][r] = (4 * fq + r <= fr) ? P[Jt][r] : 0.f; }
;                 } }
; #pragma unroll
;             for (int s = 0; s < 2; ++s) if (2 * s <= I) {
;                 u32x4 pw; pw.x = pk2(P[2 * s][0], P[2 * s][1]); pw.y = pk2(P[2 * s][2], P[2 * s][3]); pw.z = pk2(P[2 * s + 1][0], P[2 * s + 1][1]); pw.w = pk2(P[2 * s + 1][2], P[2 * s + 1][3]);
;                 const s16x4 v0 = *(const LAS s16x4*)(VT + (16 * wave + fr) * RS64 + 32 * s + 4 * fq), v1 = *(const LAS s16x4*)(VT + (16 * wave + fr) * RS64 + 32 * s + 16 + 4 * fq);
;                 const bf16x8 a = (bf16x8){v0[0], v0[1], v0[2], v0[3], v1[0], v1[1], v1[2], v1[3]};
;                 acc[I] = __builtin_amdgcn_mfma_f32_16x16x32_bf16(a, __builtin_bit_cast(bf16x8, pw), acc[I], 0, 0, 0); }
;         }
; #pragma unroll
;         for (int I = 0; I < 4; ++I) *(f32x4*)(O0 + (size_t)(m0 + 16 * I + fr) * 1024 + h * 128 + 16 * wave + 4 * fq) = acc[I];
	v_mfma_f32_16x16x32_bf16 v[24:27], v[24:27], v[82:85], 0
	s_waitcnt lgkmcnt(11)
	v_mfma_f32_16x16x32_bf16 v[24:27], v[86:89], v[90:93], v[24:27]
	ds_read_b128 v[224:227], v79 offset:56768
	s_waitcnt lgkmcnt(10)
	v_mfma_f32_16x16x32_bf16 v[24:27], v[192:195], v[94:97], v[24:27]
	s_waitcnt lgkmcnt(8)
	v_mfma_f32_16x16x32_bf16 v[24:27], v[196:199], v[98:101], v[24:27]
	s_waitcnt lgkmcnt(6)
	v_mfma_f32_16x16x32_bf16 v[86:89], v[200:203], v[82:85], 0
	s_nop 5
	v_cvt_pk_bf16_f32 v24, v24, v25
	v_cvt_pk_bf16_f32 v25, v26, v27
	v_mfma_f32_16x16x32_bf16 v[86:89], v[102:105], v[90:93], v[86:89]
	s_waitcnt lgkmcnt(5)
	v_mfma_f32_16x16x32_bf16 v[86:89], v[204:207], v[94:97], v[86:89]
	s_waitcnt lgkmcnt(4)
	v_mfma_f32_16x16x32_bf16 v[86:89], v[208:211], v[98:101], v[86:89]
	s_nop 7
	v_cvt_pk_bf16_f32 v26, v86, v87
	s_waitcnt lgkmcnt(3)
	v_mfma_f32_16x16x32_bf16 v[82:85], v[212:215], v[82:85], 0
	v_cvt_pk_bf16_f32 v27, v88, v89
	s_waitcnt lgkmcnt(2)
	v_mfma_f32_16x16x32_bf16 v[82:85], v[216:219], v[90:93], v[82:85]
	s_waitcnt lgkmcnt(1)
	v_mfma_f32_16x16x32_bf16 v[82:85], v[220:223], v[94:97], v[82:85]
	v_mfma_f32_16x16x32_bf16 v[20:23], v[12:15], v[24:27], v[20:23]
	ds_read2_b64 v[24:27], v81 offset0:8 offset1:12
	s_waitcnt lgkmcnt(1)
	v_mfma_f32_16x16x32_bf16 v[82:85], v[224:227], v[98:101], v[82:85]
	s_nop 7
	v_cndmask_b32_e64 v82, v82, 0, s[20:21]
	v_cndmask_b32_e64 v83, 0, v83, s[22:23]
	v_cndmask_b32_e64 v84, v84, 0, s[24:25]
	v_cndmask_b32_e64 v85, v85, 0, s[26:27]
	v_cvt_pk_bf16_f32 v82, v82, v83
	v_cvt_pk_bf16_f32 v83, v84, v85
	v_mov_b32_e32 v84, v3
	v_mov_b32_e32 v85, v3
	s_waitcnt lgkmcnt(0)
	s_nop 0
	v_mfma_f32_16x16x32_bf16 v[20:23], v[24:27], v[82:85], v[20:23]
	ds_read_b128 v[82:85], v79 offset:60928
	ds_read_b128 v[86:89], v79 offset:13056
	ds_read_b128 v[90:93], v79 offset:60992
	ds_read_b128 v[94:97], v79 offset:13120
	s_waitcnt lgkmcnt(2)
	v_mfma_f32_16x16x32_bf16 v[82:85], v[82:85], v[86:89], 0
	s_waitcnt lgkmcnt(0)
	v_mfma_f32_16x16x32_bf16 v[82:85], v[90:93], v[94:97], v[82:85]
	ds_read_b128 v[90:93], v79 offset:61056
	ds_read_b128 v[98:101], v79 offset:13184
	s_waitcnt lgkmcnt(0)
	v_mfma_f32_16x16x32_bf16 v[82:85], v[90:93], v[98:101], v[82:85]
	ds_read_b128 v[90:93], v79 offset:61120
	ds_read_b128 v[102:105], v79 offset:13248
	ds_read_b128 v[106:109], v79 offset:65344
	ds_read_b128 v[110:113], v80 offset:34880
	s_waitcnt lgkmcnt(2)
	v_mfma_f32_16x16x32_bf16 v[82:85], v[90:93], v[102:105], v[82:85]
	ds_read_b128 v[90:93], v79 offset:65280
	s_waitcnt lgkmcnt(0)
	v_mfma_f32_16x16x32_bf16 v[90:93], v[90:93], v[86:89], 0
	s_nop 4
	v_cvt_pk_bf16_f32 v82, v82, v83
	v_cvt_pk_bf16_f32 v83, v84, v85
	v_mfma_f32_16x16x32_bf16 v[90:93], v[106:109], v[94:97], v[90:93]
	ds_read_b128 v[106:109], v79 offset:65408
	s_waitcnt lgkmcnt(0)
	v_mfma_f32_16x16x32_bf16 v[90:93], v[106:109], v[98:101], v[90:93]
	ds_read_b128 v[106:109], v79 offset:65472
	s_waitcnt lgkmcnt(0)
	v_mfma_f32_16x16x32_bf16 v[90:93], v[106:109], v[102:105], v[90:93]
	ds_read_b128 v[106:109], v80 offset:34816
	s_nop 6
	v_cvt_pk_bf16_f32 v84, v90, v91
	s_waitcnt lgkmcnt(0)
	v_mfma_f32_16x16x32_bf16 v[106:109], v[106:109], v[86:89], 0
	v_cvt_pk_bf16_f32 v85, v92, v93
	v_mfma_f32_16x16x32_bf16 v[106:109], v[110:113], v[94:97], v[106:109]
	ds_read_b128 v[110:113], v80 offset:34944
	s_waitcnt lgkmcnt(0)
	v_mfma_f32_16x16x32_bf16 v[106:109], v[110:113], v[98:101], v[106:109]
	ds_read_b128 v[110:113], v80 offset:35008
	s_waitcnt lgkmcnt(0)
	v_mfma_f32_16x16x32_bf16 v[106:109], v[110:113], v[102:105], v[106:109]
	ds_read_b128 v[110:113], v80 offset:39168
	s_waitcnt lgkmcnt(0)
	v_mfma_f32_16x16x32_bf16 v[86:89], v[110:113], v[86:89], 0
	ds_read_b128 v[110:113], v80 offset:39232
	s_waitcnt lgkmcnt(0)
	v_mfma_f32_16x16x32_bf16 v[86:89], v[110:113], v[94:97], v[86:89]
	ds_read_b128 v[94:97], v80 offset:39296
	s_waitcnt lgkmcnt(0)
	v_mfma_f32_16x16x32_bf16 v[86:89], v[94:97], v[98:101], v[86:89]
	ds_read_b128 v[94:97], v80 offset:39360
	s_waitcnt lgkmcnt(0)
	v_mfma_f32_16x16x32_bf16 v[86:89], v[94:97], v[102:105], v[86:89]
	s_nop 7
	v_cndmask_b32_e64 v86, v86, 0, s[20:21]
	v_mfma_f32_16x16x32_bf16 v[4:7], v[12:15], v[82:85], v[4:7]
	v_cndmask_b32_e64 v87, 0, v87, s[22:23]
	v_cndmask_b32_e64 v88, v88, 0, s[24:25]
	v_cndmask_b32_e64 v89, v89, 0, s[26:27]
	v_cvt_pk_bf16_f32 v12, v106, v107
	v_cvt_pk_bf16_f32 v13, v108, v109
	v_cvt_pk_bf16_f32 v14, v86, v87
	v_cvt_pk_bf16_f32 v15, v88, v89
	s_nop 1
	v_mfma_f32_16x16x32_bf16 v[4:7], v[24:27], v[12:15], v[4:7]
	v_or_b32_e32 v12, s35, v52
	v_ashrrev_i32_e32 v13, 31, v12
	v_lshl_add_u64 v[14:15], s[52:53], 2, v[28:29]
	v_lshlrev_b64 v[24:25], 12, v[12:13]
	v_lshl_add_u64 v[24:25], v[14:15], 0, v[24:25]
	global_store_dwordx4 v[24:25], v[8:11], off
	s_nop 1
	v_or_b32_e32 v8, 16, v12
	v_ashrrev_i32_e32 v9, 31, v8
	v_lshlrev_b64 v[8:9], 12, v[8:9]
	v_lshl_add_u64 v[8:9], v[14:15], 0, v[8:9]
	global_store_dwordx4 v[8:9], v[16:19], off
	v_or_b32_e32 v8, 32, v12
	v_ashrrev_i32_e32 v9, 31, v8
	v_lshlrev_b64 v[8:9], 12, v[8:9]
	v_lshl_add_u64 v[8:9], v[14:15], 0, v[8:9]
	global_store_dwordx4 v[8:9], v[20:23], off
	v_or_b32_e32 v8, 48, v12
	v_ashrrev_i32_e32 v9, 31, v8
	v_lshlrev_b64 v[8:9], 12, v[8:9]
	v_lshl_add_u64 v[8:9], v[14:15], 0, v[8:9]
	global_store_dwordx4 v[8:9], v[4:7], off
	s_cbranch_scc0 .LBB0_887
